# ffn_up epilogue: conv-weight loads issued before the LDS barrier instead of after
# speedup vs baseline: 1.0280x; 1.0024x over previous
; __device__ __forceinline__ void phase_ffn_up(const P& p, int layer, char* lds) {
;     ...
;     __syncthreads();
;     const int f = tn * 64 + wc * 32 + r32;
;     const float w0 = p.conv_w[(layer * 3 + 0) * DFF + f], w1 = p.conv_w[(layer * 3 + 1) * DFF + f], w2 = p.conv_w[(layer * 3 + 2) * DFF + f];
;     const float cb = p.conv_b[layer * DFF + f];
;     const unsigned ob = (unsigned)(tm * 128) * DFF + f;
; #pragma unroll
;     for (int mi = 0; mi < 2; ++mi) {
;       float gp[16], gn[16];
; #pragma unroll
;       for (int r = 0; r < 16; ++r) { const int lr = lb0 + mi * 32 + (r & 3) + 8 * (r >> 2); gp[r] = Gc[lr * 65]; gn[r] = Gc[(lr + 2) * 65]; }
; #pragma unroll
;       for (int r = 0; r < 16; r += 2) {
;         const int lr = lb0 + mi * 32 + (r & 3) + 8 * (r >> 2);
;         const float g0 = fmaf(w0, gp[r], fmaf(w1, acc[mi][0][r], fmaf(w2, gn[r], cb)));
;         const float g1 = fmaf(w0, gp[r + 1], fmaf(w1, acc[mi][0][r + 1], fmaf(w2, gn[r + 1], cb)));
;         const unsigned w = cvtpk(gelu_t(g0) * acc[mi][1][r], gelu_t(g1) * acc[mi][1][r + 1]);
;         aout[ob + (unsigned)lr * DFF] = (u16)w; aout[ob + (unsigned)(lr + 1) * DFF] = (u16)(w >> 16);
;       }
.LBB0_165:
	s_or_b64 exec, exec, s[6:7]
	v_readlane_b32 s42, v255, 8
	v_or_b32_e32 v68, s8, v101
	s_mul_i32 s6, s42, 0x2100
	v_add_u32_e32 v64, s6, v68
	v_ashrrev_i32_e32 v65, 31, v64
	v_lshl_add_u64 v[66:67], v[64:65], 2, s[60:61]
	global_load_dword v78, v[66:67], off
	v_add_u32_e32 v66, 0xb00, v64
	v_ashrrev_i32_e32 v67, 31, v66
	v_lshl_add_u64 v[66:67], v[66:67], 2, s[60:61]
	s_mul_i32 s6, s42, 0xffffea00
	global_load_dword v79, v[66:67], off
	v_add_u32_e32 v66, 0x1600, v64
	v_add_u32_e32 v64, s6, v64
	v_ashrrev_i32_e32 v67, 31, v66
	v_ashrrev_i32_e32 v65, 31, v64
	v_lshl_add_u64 v[66:67], v[66:67], 2, s[60:61]
	v_lshl_add_u64 v[64:65], v[64:65], 2, s[62:63]
	global_load_dword v83, v[66:67], off
	global_load_dword v82, v[64:65], off
	s_waitcnt lgkmcnt(0)
	s_barrier
	ds_read2_b32 v[98:99], v86 offset1:65
	ds_read2_b32 v[102:103], v86 offset0:130 offset1:195
	v_add_u32_e32 v64, 0x400, v86
	ds_read2_b32 v[104:105], v64 offset0:4 offset1:69
	v_add_u32_e32 v64, 0xffffedb8, v96
	s_mul_i32 s6, s92, 0x58000
	v_add_u32_e32 v65, 0x800, v64
	v_add_u32_e32 v85, s6, v68
	ds_read2_b32 v[76:77], v94 offset0:8 offset1:73
	ds_read_b32 v94, v64 offset:520
	ds_read2_b32 v[74:75], v93 offset0:75 offset1:140
	ds_read_b32 v95, v86 offset:3380
	ds_read2_b32 v[68:69], v65 offset0:8 offset1:138
	ds_read2_b32 v[70:71], v92 offset0:81 offset1:211
	v_add_u32_e32 v65, 0x1400, v86
	ds_read2_b32 v[72:73], v65 offset0:20 offset1:85
	ds_read_b32 v93, v64 offset:4160
	ds_read_b32 v92, v96
	ds_read2_b32 v[64:65], v97 offset0:89 offset1:219
	v_add_u32_e32 v84, 0xb00, v85
	v_add_u32_e32 v66, 0x1c00, v86
	ds_read2_b32 v[66:67], v66 offset0:28 offset1:93
	v_readlane_b32 s43, v255, 9
	s_waitcnt vmcnt(0) lgkmcnt(12)
	v_fma_f32 v96, v83, v102, v82
	v_fmac_f32_e32 v96, v79, v48
	v_fmac_f32_e32 v96, v78, v98
	v_fma_f32 v48, v83, v103, v82
	v_fmac_f32_e32 v48, v79, v49
	v_mul_f32_e32 v49, v96, v96
	v_fmamk_f32 v49, v49, 0xbdd2d3e7, v215
	v_mul_f32_e32 v49, v96, v49
	v_exp_f32_e32 v49, v49
	v_fmac_f32_e32 v48, v78, v99
	v_add_f32_e32 v49, 1.0, v49
	v_rcp_f32_e32 v49, v49
	s_nop 0
	v_mul_f32_e32 v49, v96, v49
	v_mul_f32_e32 v32, v32, v49
	v_mul_f32_e32 v49, v48, v48
	v_fmamk_f32 v49, v49, 0xbdd2d3e7, v215
	v_mul_f32_e32 v49, v48, v49
	v_exp_f32_e32 v49, v49
	s_nop 0
	v_add_f32_e32 v49, 1.0, v49
	v_rcp_f32_e32 v49, v49
	s_nop 0
	v_mul_f32_e32 v48, v48, v49
	v_mul_f32_e32 v33, v33, v48
	v_mul_lo_u32 v48, v87, s11
	v_add_u32_e32 v200, v48, v85
	v_cvt_pk_bf16_f32 v49, v32, v33
	v_lshl_add_u64 v[32:33], v[200:201], 1, s[82:83]
	v_add_u32_e32 v200, v48, v84
	global_store_short v[32:33], v49, off
	v_lshl_add_u64 v[32:33], v[200:201], 1, s[82:83]
	global_store_short_d16_hi v[32:33], v49, off
	s_waitcnt lgkmcnt(11)
	v_fma_f32 v32, v83, v104, v82
	v_fmac_f32_e32 v32, v79, v50
	v_fmac_f32_e32 v32, v78, v102
	v_mul_f32_e32 v49, v32, v32
	v_fmamk_f32 v49, v49, 0xbdd2d3e7, v215
	v_mul_f32_e32 v49, v32, v49
	v_exp_f32_e32 v49, v49
	v_fma_f32 v33, v83, v105, v82
	v_fmac_f32_e32 v33, v79, v51
	v_fmac_f32_e32 v33, v78, v103
	v_add_f32_e32 v49, 1.0, v49
	v_rcp_f32_e32 v49, v49
	s_nop 0
	v_mul_f32_e32 v32, v32, v49
	v_mul_f32_e32 v32, v34, v32
	v_mul_f32_e32 v34, v33, v33
	v_fmamk_f32 v34, v34, 0xbdd2d3e7, v215
	v_mul_f32_e32 v34, v33, v34
	v_exp_f32_e32 v34, v34
	s_nop 0
	v_add_f32_e32 v34, 1.0, v34
	v_rcp_f32_e32 v34, v34
	s_nop 0
	v_mul_f32_e32 v33, v33, v34
	v_mul_f32_e32 v33, v35, v33
	v_add_u32_e32 v35, 0x1600, v48
	v_add_u32_e32 v200, v35, v85
	v_cvt_pk_bf16_f32 v34, v32, v33
	v_lshl_add_u64 v[32:33], v[200:201], 1, s[82:83]
	v_add_u32_e32 v200, v35, v84
	global_store_short v[32:33], v34, off
	v_lshl_add_u64 v[32:33], v[200:201], 1, s[82:83]
	global_store_short_d16_hi v[32:33], v34, off
	s_waitcnt lgkmcnt(9)
	v_fma_f32 v32, v83, v94, v82
	v_fmac_f32_e32 v32, v79, v52
	v_fmac_f32_e32 v32, v78, v76
	v_mul_f32_e32 v34, v32, v32
	v_fmamk_f32 v34, v34, 0xbdd2d3e7, v215
	v_mul_f32_e32 v34, v32, v34
	v_exp_f32_e32 v34, v34
	s_waitcnt lgkmcnt(8)
	v_fma_f32 v33, v83, v74, v82
	v_fmac_f32_e32 v33, v79, v53
	v_fmac_f32_e32 v33, v78, v77
	v_add_f32_e32 v34, 1.0, v34
	v_rcp_f32_e32 v34, v34
	v_add_u32_e32 v35, 0x5800, v48
	v_add_u32_e32 v200, v35, v85
	v_mul_f32_e32 v32, v32, v34
	v_mul_f32_e32 v34, v33, v33
	v_fmamk_f32 v34, v34, 0xbdd2d3e7, v215
	v_mul_f32_e32 v34, v33, v34
	v_exp_f32_e32 v34, v34
	v_mul_f32_e32 v32, v36, v32
	v_add_f32_e32 v34, 1.0, v34
	v_rcp_f32_e32 v34, v34
	s_nop 0
	v_mul_f32_e32 v33, v33, v34
	v_mul_f32_e32 v33, v37, v33
	v_cvt_pk_bf16_f32 v34, v32, v33
	v_lshl_add_u64 v[32:33], v[200:201], 1, s[82:83]
	v_add_u32_e32 v200, v35, v84
	global_store_short v[32:33], v34, off
	v_lshl_add_u64 v[32:33], v[200:201], 1, s[82:83]
	global_store_short_d16_hi v[32:33], v34, off
	v_fma_f32 v32, v83, v75, v82
	v_fmac_f32_e32 v32, v79, v54
	v_fmac_f32_e32 v32, v78, v94
	v_mul_f32_e32 v34, v32, v32
	v_fmamk_f32 v34, v34, 0xbdd2d3e7, v215
	v_mul_f32_e32 v34, v32, v34
	v_exp_f32_e32 v34, v34
	s_waitcnt lgkmcnt(7)
	v_fma_f32 v33, v83, v95, v82
	v_fmac_f32_e32 v33, v79, v55
	v_fmac_f32_e32 v33, v78, v74
	v_add_f32_e32 v34, 1.0, v34
	v_rcp_f32_e32 v34, v34
	v_add_u32_e32 v35, 0x6e00, v48
	v_add_u32_e32 v200, v35, v85
	v_mul_f32_e32 v32, v32, v34
	v_mul_f32_e32 v34, v33, v33
	v_fmamk_f32 v34, v34, 0xbdd2d3e7, v215
	v_mul_f32_e32 v34, v33, v34
	v_exp_f32_e32 v34, v34
	v_mul_f32_e32 v32, v38, v32
	v_add_f32_e32 v34, 1.0, v34
	v_rcp_f32_e32 v34, v34
	s_nop 0
	v_mul_f32_e32 v33, v33, v34
	v_mul_f32_e32 v33, v39, v33
	v_cvt_pk_bf16_f32 v34, v32, v33
	v_lshl_add_u64 v[32:33], v[200:201], 1, s[82:83]
	v_add_u32_e32 v200, v35, v84
	global_store_short v[32:33], v34, off
	v_lshl_add_u64 v[32:33], v[200:201], 1, s[82:83]
	global_store_short_d16_hi v[32:33], v34, off
	s_waitcnt lgkmcnt(6)
; #define SBAR() __builtin_amdgcn_sched_barrier(0)
; __device__ __forceinline__ void phase_ffn_up(const P& p, int layer, char* lds) {
;     ...
;     for (int mi = 0; mi < 2; ++mi) {
;       float gp[16], gn[16];
; #pragma unroll
;       for (int r = 0; r < 16; ++r) { const int lr = lb0 + mi * 32 + (r & 3) + 8 * (r >> 2); gp[r] = Gc[lr * 65]; gn[r] = Gc[(lr + 2) * 65]; }
; #pragma unroll
;       for (int r = 0; r < 16; r += 2) {
;         const int lr = lb0 + mi * 32 + (r & 3) + 8 * (r >> 2);
;         const float g0 = fmaf(w0, gp[r], fmaf(w1, acc[mi][0][r], fmaf(w2, gn[r], cb)));
;         const float g1 = fmaf(w0, gp[r + 1], fmaf(w1, acc[mi][0][r + 1], fmaf(w2, gn[r + 1], cb)));
;         const unsigned w = cvtpk(gelu_t(g0) * acc[mi][1][r], gelu_t(g1) * acc[mi][1][r + 1]);
;         aout[ob + (unsigned)lr * DFF] = (u16)w; aout[ob + (unsigned)(lr + 1) * DFF] = (u16)(w >> 16);
;       }
;       SBAR();
	v_fma_f32 v32, v83, v69, v82
	v_fmac_f32_e32 v32, v79, v56
	v_fmac_f32_e32 v32, v78, v68
	v_mul_f32_e32 v34, v32, v32
	v_fmamk_f32 v34, v34, 0xbdd2d3e7, v215
	v_mul_f32_e32 v34, v32, v34
	v_exp_f32_e32 v34, v34
	s_waitcnt lgkmcnt(5)
	v_fma_f32 v33, v83, v71, v82
	v_fmac_f32_e32 v33, v79, v57
	v_fmac_f32_e32 v33, v78, v70
	v_add_f32_e32 v34, 1.0, v34
	v_rcp_f32_e32 v34, v34
	v_add_u32_e32 v35, 0xb000, v48
	v_add_u32_e32 v200, v35, v85
	v_mul_f32_e32 v32, v32, v34
	v_mul_f32_e32 v34, v33, v33
	v_fmamk_f32 v34, v34, 0xbdd2d3e7, v215
	v_mul_f32_e32 v34, v33, v34
	v_exp_f32_e32 v34, v34
	v_mul_f32_e32 v32, v40, v32
	v_add_f32_e32 v34, 1.0, v34
	v_rcp_f32_e32 v34, v34
	s_nop 0
	v_mul_f32_e32 v33, v33, v34
	v_mul_f32_e32 v33, v41, v33
	v_cvt_pk_bf16_f32 v34, v32, v33
	v_lshl_add_u64 v[32:33], v[200:201], 1, s[82:83]
	v_add_u32_e32 v200, v35, v84
	global_store_short v[32:33], v34, off
	v_lshl_add_u64 v[32:33], v[200:201], 1, s[82:83]
	global_store_short_d16_hi v[32:33], v34, off
	s_waitcnt lgkmcnt(4)
	v_fma_f32 v32, v83, v72, v82
	v_fmac_f32_e32 v32, v79, v58
	v_fmac_f32_e32 v32, v78, v69
	v_mul_f32_e32 v34, v32, v32
	v_fmamk_f32 v34, v34, 0xbdd2d3e7, v215
	v_mul_f32_e32 v34, v32, v34
	v_exp_f32_e32 v34, v34
	v_fma_f32 v33, v83, v73, v82
	v_fmac_f32_e32 v33, v79, v59
	v_fmac_f32_e32 v33, v78, v71
	v_add_f32_e32 v34, 1.0, v34
	v_rcp_f32_e32 v34, v34
	v_add_u32_e32 v35, 0xc600, v48
	v_add_u32_e32 v200, v35, v85
	v_mul_f32_e32 v32, v32, v34
	v_mul_f32_e32 v34, v33, v33
	v_fmamk_f32 v34, v34, 0xbdd2d3e7, v215
	v_mul_f32_e32 v34, v33, v34
	v_exp_f32_e32 v34, v34
	v_mul_f32_e32 v32, v42, v32
	v_add_f32_e32 v34, 1.0, v34
	v_rcp_f32_e32 v34, v34
	s_nop 0
	v_mul_f32_e32 v33, v33, v34
	v_mul_f32_e32 v33, v43, v33
	v_cvt_pk_bf16_f32 v34, v32, v33
	v_lshl_add_u64 v[32:33], v[200:201], 1, s[82:83]
	v_add_u32_e32 v200, v35, v84
	global_store_short v[32:33], v34, off
	v_lshl_add_u64 v[32:33], v[200:201], 1, s[82:83]
	global_store_short_d16_hi v[32:33], v34, off
	s_waitcnt lgkmcnt(2)
	v_fma_f32 v32, v83, v92, v82
	v_fmac_f32_e32 v32, v79, v60
	v_fmac_f32_e32 v32, v78, v93
	v_mul_f32_e32 v34, v32, v32
	v_fmamk_f32 v34, v34, 0xbdd2d3e7, v215
	v_mul_f32_e32 v34, v32, v34
	v_exp_f32_e32 v34, v34
	s_waitcnt lgkmcnt(1)
	v_fma_f32 v33, v83, v65, v82
	v_fmac_f32_e32 v33, v79, v61
	v_fmac_f32_e32 v33, v78, v64
	v_add_f32_e32 v34, 1.0, v34
	v_rcp_f32_e32 v34, v34
	v_add_u32_e32 v35, 0x10800, v48
	v_add_u32_e32 v200, v35, v85
	v_mul_f32_e32 v32, v32, v34
	v_mul_f32_e32 v34, v33, v33
	v_fmamk_f32 v34, v34, 0xbdd2d3e7, v215
	v_mul_f32_e32 v34, v33, v34
	v_exp_f32_e32 v34, v34
	v_mul_f32_e32 v32, v44, v32
	v_add_f32_e32 v34, 1.0, v34
	v_rcp_f32_e32 v34, v34
	s_nop 0
	v_mul_f32_e32 v33, v33, v34
	v_mul_f32_e32 v33, v45, v33
	v_cvt_pk_bf16_f32 v34, v32, v33
	v_lshl_add_u64 v[32:33], v[200:201], 1, s[82:83]
	v_add_u32_e32 v200, v35, v84
	global_store_short v[32:33], v34, off
	v_lshl_add_u64 v[32:33], v[200:201], 1, s[82:83]
	global_store_short_d16_hi v[32:33], v34, off
	s_waitcnt lgkmcnt(0)
	v_fma_f32 v32, v83, v66, v82
	v_fmac_f32_e32 v32, v79, v62
	v_fmac_f32_e32 v32, v78, v92
	v_mul_f32_e32 v34, v32, v32
	v_fmamk_f32 v34, v34, 0xbdd2d3e7, v215
	v_mul_f32_e32 v34, v32, v34
	v_exp_f32_e32 v34, v34
	v_fma_f32 v33, v83, v67, v82
	v_fmac_f32_e32 v33, v79, v63
	v_fmac_f32_e32 v33, v78, v65
	v_add_f32_e32 v34, 1.0, v34
	v_rcp_f32_e32 v34, v34
	v_add_u32_e32 v35, 0x11e00, v48
	v_add_u32_e32 v200, v35, v85
	v_mul_f32_e32 v32, v32, v34
	v_mul_f32_e32 v34, v33, v33
	v_fmamk_f32 v34, v34, 0xbdd2d3e7, v215
	v_mul_f32_e32 v34, v33, v34
	v_exp_f32_e32 v34, v34
	v_mul_f32_e32 v32, v46, v32
	v_add_f32_e32 v34, 1.0, v34
	v_rcp_f32_e32 v34, v34
	s_nop 0
	v_mul_f32_e32 v33, v33, v34
	v_mul_f32_e32 v33, v47, v33
	v_cvt_pk_bf16_f32 v34, v32, v33
	v_lshl_add_u64 v[32:33], v[200:201], 1, s[82:83]
	v_add_u32_e32 v200, v35, v84
	global_store_short v[32:33], v34, off
	v_lshl_add_u64 v[32:33], v[200:201], 1, s[82:83]
	global_store_short_d16_hi v[32:33], v34, off
	s_movk_i32 s6, 0x104
	v_mad_u64_u32 v[34:35], s[6:7], v87, s6, v[80:81]
	v_add_u32_e32 v32, 0x2000, v34
	ds_read2_b32 v[36:37], v32 offset0:32 offset1:162
	ds_read2_b32 v[38:39], v89 offset0:97 offset1:227
	v_add_u32_e32 v32, 0x2800, v34
	ds_read2_b32 v[40:41], v32 offset0:40 offset1:170
	ds_read2_b32 v[42:43], v91 offset0:105 offset1:235
	v_add_u32_e32 v32, 0x3000, v34
	s_waitcnt lgkmcnt(3)
	v_fma_f32 v35, v83, v37, v82
	v_fmac_f32_e32 v35, v79, v16
	v_fmac_f32_e32 v35, v78, v36
	s_waitcnt lgkmcnt(2)
	v_fma_f32 v36, v83, v39, v82
	v_mul_f32_e32 v16, v35, v35
	v_fmac_f32_e32 v36, v79, v17
	v_fmamk_f32 v16, v16, 0xbdd2d3e7, v215
	v_fmac_f32_e32 v36, v78, v38
	v_mul_f32_e32 v16, v35, v16
	v_exp_f32_e32 v38, v16
	v_mul_f32_e32 v16, v36, v36
	v_fmamk_f32 v16, v16, 0xbdd2d3e7, v215
	v_mul_f32_e32 v16, v36, v16
	v_exp_f32_e32 v49, v16
	v_add_f32_e32 v38, 1.0, v38
	v_rcp_f32_e32 v38, v38
	ds_read2_b32 v[44:45], v32 offset0:48 offset1:178
	ds_read2_b32 v[46:47], v90 offset0:113 offset1:243
	v_add_f32_e32 v49, 1.0, v49
	v_rcp_f32_e32 v49, v49
	v_mul_f32_e32 v35, v35, v38
	v_mul_f32_e32 v0, v0, v35
	v_add_u32_e32 v32, 0x3800, v34
	v_mul_f32_e32 v35, v36, v49
	v_add_u32_e32 v36, 0x16000, v48
	v_mul_f32_e32 v1, v1, v35
	v_add_u32_e32 v200, v36, v85
	ds_read2_b32 v[32:33], v32 offset0:56 offset1:186
	ds_read2_b32 v[16:17], v88 offset0:121 offset1:251
	ds_read_b32 v50, v34 offset:9360
	ds_read_b32 v51, v86 offset:9620
	ds_read_b32 v52, v34 offset:11440
	ds_read_b32 v53, v86 offset:11700
	ds_read_b32 v54, v34 offset:13520
	ds_read_b32 v55, v86 offset:13780
	ds_read_b32 v34, v34 offset:15600
	ds_read_b32 v56, v86 offset:15860
	v_cvt_pk_bf16_f32 v35, v0, v1
	v_lshl_add_u64 v[0:1], v[200:201], 1, s[82:83]
	v_add_u32_e32 v200, v36, v84
	s_waitcnt lgkmcnt(7)
; #define SBAR() __builtin_amdgcn_sched_barrier(0)
; __device__ __forceinline__ void phase_ffn_up(const P& p, int layer, char* lds) {
;     ...
;     for (int mi = 0; mi < 2; ++mi) {
;       float gp[16], gn[16];
; #pragma unroll
;       for (int r = 0; r < 16; ++r) { const int lr = lb0 + mi * 32 + (r & 3) + 8 * (r >> 2); gp[r] = Gc[lr * 65]; gn[r] = Gc[(lr + 2) * 65]; }
; #pragma unroll
;       for (int r = 0; r < 16; r += 2) {
;         const int lr = lb0 + mi * 32 + (r & 3) + 8 * (r >> 2);
;         const float g0 = fmaf(w0, gp[r], fmaf(w1, acc[mi][0][r], fmaf(w2, gn[r], cb)));
;         const float g1 = fmaf(w0, gp[r + 1], fmaf(w1, acc[mi][0][r + 1], fmaf(w2, gn[r + 1], cb)));
;         const unsigned w = cvtpk(gelu_t(g0) * acc[mi][1][r], gelu_t(g1) * acc[mi][1][r + 1]);
;         aout[ob + (unsigned)lr * DFF] = (u16)w; aout[ob + (unsigned)(lr + 1) * DFF] = (u16)(w >> 16);
;       }
;       SBAR();
;     }
	v_fma_f32 v36, v83, v50, v82
	v_fmac_f32_e32 v36, v79, v18
	v_fmac_f32_e32 v36, v78, v37
	global_store_short v[0:1], v35, off
	s_waitcnt lgkmcnt(6)
	v_fma_f32 v18, v83, v51, v82
	v_mul_f32_e32 v0, v36, v36
	v_fmac_f32_e32 v18, v79, v19
	v_fmamk_f32 v0, v0, 0xbdd2d3e7, v215
	v_fmac_f32_e32 v18, v78, v39
	v_mul_f32_e32 v0, v36, v0
	v_exp_f32_e32 v19, v0
	v_mul_f32_e32 v0, v18, v18
	v_fmamk_f32 v0, v0, 0xbdd2d3e7, v215
	v_mul_f32_e32 v0, v18, v0
	v_exp_f32_e32 v37, v0
	v_add_f32_e32 v19, 1.0, v19
	v_rcp_f32_e32 v19, v19
	v_lshl_add_u64 v[0:1], v[200:201], 1, s[82:83]
	v_add_f32_e32 v37, 1.0, v37
	v_rcp_f32_e32 v37, v37
	global_store_short_d16_hi v[0:1], v35, off
	v_mul_f32_e32 v0, v36, v19
	v_mul_f32_e32 v0, v2, v0
	v_mul_f32_e32 v1, v18, v37
	v_mul_f32_e32 v1, v3, v1
	v_add_u32_e32 v3, 0x17600, v48
	v_add_u32_e32 v200, v3, v85
	v_cvt_pk_bf16_f32 v2, v0, v1
	v_lshl_add_u64 v[0:1], v[200:201], 1, s[82:83]
	v_add_u32_e32 v200, v3, v84
	v_fma_f32 v3, v83, v41, v82
	v_fmac_f32_e32 v3, v79, v20
	v_fmac_f32_e32 v3, v78, v40
	global_store_short v[0:1], v2, off
	v_fma_f32 v18, v83, v43, v82
	v_mul_f32_e32 v0, v3, v3
	v_fmac_f32_e32 v18, v79, v21
	v_fmamk_f32 v0, v0, 0xbdd2d3e7, v215
	v_fmac_f32_e32 v18, v78, v42
	v_mul_f32_e32 v0, v3, v0
	v_exp_f32_e32 v19, v0
	v_mul_f32_e32 v0, v18, v18
	v_fmamk_f32 v0, v0, 0xbdd2d3e7, v215
	v_mul_f32_e32 v0, v18, v0
	v_exp_f32_e32 v20, v0
	v_add_f32_e32 v19, 1.0, v19
	v_rcp_f32_e32 v19, v19
	v_lshl_add_u64 v[0:1], v[200:201], 1, s[82:83]
	v_add_f32_e32 v20, 1.0, v20
	v_rcp_f32_e32 v20, v20
	global_store_short_d16_hi v[0:1], v2, off
	v_mul_f32_e32 v0, v3, v19
	v_add_u32_e32 v3, 0x1b800, v48
	v_mul_f32_e32 v1, v18, v20
	v_mul_f32_e32 v0, v4, v0
	v_mul_f32_e32 v1, v5, v1
	v_add_u32_e32 v200, v3, v85
	v_cvt_pk_bf16_f32 v2, v0, v1
	v_lshl_add_u64 v[0:1], v[200:201], 1, s[82:83]
	v_add_u32_e32 v200, v3, v84
	s_waitcnt lgkmcnt(5)
	v_fma_f32 v3, v83, v52, v82
	v_fmac_f32_e32 v3, v79, v22
	v_fmac_f32_e32 v3, v78, v41
	global_store_short v[0:1], v2, off
	s_waitcnt lgkmcnt(4)
	v_fma_f32 v4, v83, v53, v82
	v_mul_f32_e32 v0, v3, v3
	v_fmac_f32_e32 v4, v79, v23
	v_fmamk_f32 v0, v0, 0xbdd2d3e7, v215
	v_fmac_f32_e32 v4, v78, v43
	v_mul_f32_e32 v0, v3, v0
	v_exp_f32_e32 v5, v0
	v_mul_f32_e32 v0, v4, v4
	v_fmamk_f32 v0, v0, 0xbdd2d3e7, v215
	v_mul_f32_e32 v0, v4, v0
	v_exp_f32_e32 v18, v0
	v_add_f32_e32 v5, 1.0, v5
	v_rcp_f32_e32 v5, v5
	v_lshl_add_u64 v[0:1], v[200:201], 1, s[82:83]
	v_add_f32_e32 v18, 1.0, v18
	v_rcp_f32_e32 v18, v18
	global_store_short_d16_hi v[0:1], v2, off
	v_mul_f32_e32 v0, v3, v5
	v_add_u32_e32 v3, 0x1ce00, v48
	v_mul_f32_e32 v1, v4, v18
	v_mul_f32_e32 v0, v6, v0
	v_mul_f32_e32 v1, v7, v1
	v_add_u32_e32 v200, v3, v85
	v_cvt_pk_bf16_f32 v2, v0, v1
	v_lshl_add_u64 v[0:1], v[200:201], 1, s[82:83]
	v_add_u32_e32 v200, v3, v84
	v_fma_f32 v3, v83, v45, v82
	v_fmac_f32_e32 v3, v79, v24
	v_fmac_f32_e32 v3, v78, v44
	global_store_short v[0:1], v2, off
	v_fma_f32 v4, v83, v47, v82
	v_mul_f32_e32 v0, v3, v3
	v_fmac_f32_e32 v4, v79, v25
	v_fmamk_f32 v0, v0, 0xbdd2d3e7, v215
	v_fmac_f32_e32 v4, v78, v46
	v_mul_f32_e32 v0, v3, v0
	v_exp_f32_e32 v5, v0
	v_mul_f32_e32 v0, v4, v4
	v_fmamk_f32 v0, v0, 0xbdd2d3e7, v215
	v_mul_f32_e32 v0, v4, v0
	v_exp_f32_e32 v6, v0
	v_add_f32_e32 v5, 1.0, v5
	v_rcp_f32_e32 v5, v5
	v_lshl_add_u64 v[0:1], v[200:201], 1, s[82:83]
	v_add_f32_e32 v6, 1.0, v6
	v_rcp_f32_e32 v6, v6
	global_store_short_d16_hi v[0:1], v2, off
	v_mul_f32_e32 v0, v3, v5
	v_add_u32_e32 v3, 0x21000, v48
	v_mul_f32_e32 v1, v4, v6
	v_mul_f32_e32 v0, v8, v0
	v_mul_f32_e32 v1, v9, v1
	v_add_u32_e32 v200, v3, v85
	v_cvt_pk_bf16_f32 v2, v0, v1
	v_lshl_add_u64 v[0:1], v[200:201], 1, s[82:83]
	v_add_u32_e32 v200, v3, v84
	s_waitcnt lgkmcnt(3)
	v_fma_f32 v3, v83, v54, v82
	v_fmac_f32_e32 v3, v79, v26
	v_fmac_f32_e32 v3, v78, v45
	global_store_short v[0:1], v2, off
	s_waitcnt lgkmcnt(2)
	v_fma_f32 v4, v83, v55, v82
	v_mul_f32_e32 v0, v3, v3
	v_fmac_f32_e32 v4, v79, v27
	v_fmamk_f32 v0, v0, 0xbdd2d3e7, v215
	v_fmac_f32_e32 v4, v78, v47
	v_mul_f32_e32 v0, v3, v0
	v_exp_f32_e32 v5, v0
	v_mul_f32_e32 v0, v4, v4
	v_fmamk_f32 v0, v0, 0xbdd2d3e7, v215
	v_mul_f32_e32 v0, v4, v0
	v_exp_f32_e32 v6, v0
	v_add_f32_e32 v5, 1.0, v5
	v_rcp_f32_e32 v5, v5
	v_lshl_add_u64 v[0:1], v[200:201], 1, s[82:83]
	v_add_f32_e32 v6, 1.0, v6
	v_rcp_f32_e32 v6, v6
	global_store_short_d16_hi v[0:1], v2, off
	v_mul_f32_e32 v0, v3, v5
	v_add_u32_e32 v3, 0x22600, v48
	v_mul_f32_e32 v1, v4, v6
	v_mul_f32_e32 v0, v10, v0
	v_mul_f32_e32 v1, v11, v1
	v_add_u32_e32 v200, v3, v85
	v_cvt_pk_bf16_f32 v2, v0, v1
	v_lshl_add_u64 v[0:1], v[200:201], 1, s[82:83]
	v_add_u32_e32 v200, v3, v84
	v_fma_f32 v3, v83, v33, v82
	v_fmac_f32_e32 v3, v79, v28
	v_fmac_f32_e32 v3, v78, v32
	global_store_short v[0:1], v2, off
	v_fma_f32 v4, v83, v17, v82
	v_mul_f32_e32 v0, v3, v3
	v_fmac_f32_e32 v4, v79, v29
	v_fmamk_f32 v0, v0, 0xbdd2d3e7, v215
	v_fmac_f32_e32 v4, v78, v16
	v_mul_f32_e32 v0, v3, v0
	v_exp_f32_e32 v5, v0
	v_mul_f32_e32 v0, v4, v4
	v_fmamk_f32 v0, v0, 0xbdd2d3e7, v215
	v_mul_f32_e32 v0, v4, v0
	v_exp_f32_e32 v6, v0
	v_add_f32_e32 v5, 1.0, v5
	v_rcp_f32_e32 v5, v5
	v_lshl_add_u64 v[0:1], v[200:201], 1, s[82:83]
	v_add_f32_e32 v6, 1.0, v6
	v_rcp_f32_e32 v6, v6
	global_store_short_d16_hi v[0:1], v2, off
	v_mul_f32_e32 v0, v3, v5
	v_add_u32_e32 v3, 0x26800, v48
	v_mul_f32_e32 v1, v4, v6
	v_mul_f32_e32 v0, v12, v0
	v_mul_f32_e32 v1, v13, v1
	v_add_u32_e32 v200, v3, v85
	v_cvt_pk_bf16_f32 v2, v0, v1
	v_lshl_add_u64 v[0:1], v[200:201], 1, s[82:83]
	v_add_u32_e32 v200, v3, v84
	s_waitcnt lgkmcnt(1)
	v_fma_f32 v3, v83, v34, v82
	v_fmac_f32_e32 v3, v79, v30
	v_fmac_f32_e32 v3, v78, v33
	global_store_short v[0:1], v2, off
	s_waitcnt lgkmcnt(0)
	v_fmac_f32_e32 v82, v83, v56
	v_mul_f32_e32 v0, v3, v3
	v_fmac_f32_e32 v82, v79, v31
	v_fmamk_f32 v0, v0, 0xbdd2d3e7, v215
	v_fmac_f32_e32 v82, v78, v17
	v_mul_f32_e32 v0, v3, v0
	v_exp_f32_e32 v4, v0
	v_mul_f32_e32 v0, v82, v82
	v_fmamk_f32 v0, v0, 0xbdd2d3e7, v215
	v_mul_f32_e32 v0, v82, v0
	v_exp_f32_e32 v5, v0
	v_add_f32_e32 v4, 1.0, v4
	v_rcp_f32_e32 v4, v4
	v_lshl_add_u64 v[0:1], v[200:201], 1, s[82:83]
	v_add_f32_e32 v5, 1.0, v5
	v_rcp_f32_e32 v5, v5
	global_store_short_d16_hi v[0:1], v2, off
	v_mul_f32_e32 v0, v3, v4
	v_add_u32_e32 v3, 0x27e00, v48
	v_mul_f32_e32 v1, v82, v5
	v_mul_f32_e32 v0, v14, v0
	v_mul_f32_e32 v1, v15, v1
	v_add_u32_e32 v200, v3, v85
	v_cvt_pk_bf16_f32 v2, v0, v1
	v_lshl_add_u64 v[0:1], v[200:201], 1, s[82:83]
	v_add_u32_e32 v200, v3, v84
	global_store_short v[0:1], v2, off
	v_lshl_add_u64 v[0:1], v[200:201], 1, s[82:83]
	global_store_short_d16_hi v[0:1], v2, off
	s_add_i32 s19, s19, 1
	s_mul_i32 s6, s19, s18
	s_add_i32 s6, s6, s13
	s_add_i32 s33, s33, s18
	s_cmpk_gt_u32 s33, 0x57f
	s_cbranch_scc1 .LBB0_203
